# attention: rescale factor chain (sub, mul, exp, cndmask) moved in front of the per-tile wait+barrier at the second site of both step loops
# baseline (speedup 1.0000x reference)
.LBB0_1035:
	v_exp_f32_e32 v218, v88
	v_exp_f32_e32 v225, v89
	s_add_i32 s0, s75, 1
	s_cmp_lg_u32 s75, 2
	s_cselect_b32 s76, s0, 0
	v_exp_f32_e32 v120, v80
	v_exp_f32_e32 v121, v81
	v_exp_f32_e32 v122, v82
	v_exp_f32_e32 v123, v83
	v_exp_f32_e32 v124, v84
	v_exp_f32_e32 v125, v85
	v_exp_f32_e32 v126, v86
	v_exp_f32_e32 v127, v87
	v_exp_f32_e32 v226, v90
	v_exp_f32_e32 v227, v91
	v_exp_f32_e32 v228, v92
	v_exp_f32_e32 v229, v93
	v_exp_f32_e32 v230, v94
	v_exp_f32_e32 v231, v95
	s_setprio 1
	v_lshl_add_u32 v223, s76, 13, v190
	v_add_u32_e32 v68, v223, v191
	ds_read_b128 v[64:67], v68 offset:49152
	ds_read_b128 v[68:71], v68 offset:53248
	v_add_u32_e32 v116, v223, v192
	ds_read_b128 v[112:115], v116 offset:49152
	ds_read_b128 v[116:119], v116 offset:53248
	s_waitcnt lgkmcnt(0)
	v_mfma_f32_32x32x16_bf16 v[80:95], v[64:67], v[108:111], 0
	v_mfma_f32_32x32x16_bf16 v[64:79], v[68:71], v[108:111], 0
	v_mfma_f32_32x32x16_bf16 v[80:95], v[112:115], v[104:107], v[80:95]
	v_mfma_f32_32x32x16_bf16 v[64:79], v[116:119], v[104:107], v[64:79]
	v_add_u32_e32 v116, v223, v193
	ds_read_b128 v[112:115], v116 offset:49152
	ds_read_b128 v[116:119], v116 offset:53248
	s_waitcnt lgkmcnt(0)
	v_mfma_f32_32x32x16_bf16 v[80:95], v[112:115], v[100:103], v[80:95]
	v_mfma_f32_32x32x16_bf16 v[64:79], v[116:119], v[100:103], v[64:79]
	v_add_u32_e32 v116, v223, v194
	ds_read_b128 v[112:115], v116 offset:49152
	ds_read_b128 v[116:119], v116 offset:53248
	s_waitcnt lgkmcnt(0)
	v_mfma_f32_32x32x16_bf16 v[80:95], v[112:115], v[96:99], v[80:95]
	v_mfma_f32_32x32x16_bf16 v[64:79], v[116:119], v[96:99], v[64:79]
	s_setprio 0
	v_exp_f32_e32 v160, v160
	v_exp_f32_e32 v161, v161
	v_add_f32_e32 v112, v120, v160
	v_add_f32_e32 v113, v121, v161
	v_exp_f32_e32 v162, v162
	v_add_f32_e32 v112, v112, v122
	v_add_f32_e32 v113, v113, v123
	v_exp_f32_e32 v163, v163
	v_add_f32_e32 v112, v112, v162
	v_add_f32_e32 v113, v113, v163
	v_exp_f32_e32 v164, v164
	v_add_f32_e32 v112, v112, v124
	v_add_f32_e32 v113, v113, v125
	v_exp_f32_e32 v165, v165
	v_add_f32_e32 v112, v112, v164
	v_add_f32_e32 v113, v113, v165
	v_exp_f32_e32 v166, v166
	v_add_f32_e32 v112, v112, v126
	v_add_f32_e32 v113, v113, v127
	v_exp_f32_e32 v167, v167
	v_add_f32_e32 v112, v112, v166
	v_add_f32_e32 v113, v113, v167
	v_exp_f32_e32 v168, v168
	v_add_f32_e32 v112, v112, v218
	v_add_f32_e32 v113, v113, v225
	v_exp_f32_e32 v169, v169
	v_add_f32_e32 v112, v112, v168
	v_add_f32_e32 v113, v113, v169
	v_exp_f32_e32 v170, v170
	v_add_f32_e32 v112, v112, v226
	v_add_f32_e32 v113, v113, v227
	v_exp_f32_e32 v171, v171
	v_add_f32_e32 v112, v112, v170
	v_add_f32_e32 v113, v113, v171
	v_exp_f32_e32 v172, v172
	v_add_f32_e32 v112, v112, v228
	v_add_f32_e32 v113, v113, v229
	v_exp_f32_e32 v173, v173
	v_exp_f32_e32 v174, v174
	v_exp_f32_e32 v175, v175
	v_add_f32_e32 v112, v112, v172
	v_add_f32_e32 v113, v113, v173
	s_nop 0
	v_add_f32_e32 v112, v112, v230
	v_add_f32_e32 v113, v113, v231
	s_nop 0
	v_add_f32_e32 v112, v112, v174
	v_add_f32_e32 v113, v113, v175
	s_nop 0
	v_add_f32_e32 v223, v112, v113
	v_cvt_pk_bf16_f32 v112, v120, v121
	v_cvt_pk_bf16_f32 v113, v122, v123
	v_cvt_pk_bf16_f32 v114, v124, v125
	v_cvt_pk_bf16_f32 v115, v126, v127
	v_cvt_pk_bf16_f32 v116, v218, v225
	s_nop 0
	v_mov_b32_e32 v224, v223
	s_nop 1
	v_permlane32_swap_b32_e32 v223, v224
	v_cvt_pk_bf16_f32 v117, v226, v227
	v_cvt_pk_bf16_f32 v118, v228, v229
	v_cvt_pk_bf16_f32 v119, v230, v231
	v_cvt_pk_bf16_f32 v120, v160, v161
	v_cvt_pk_bf16_f32 v121, v162, v163
	v_cvt_pk_bf16_f32 v122, v164, v165
	v_cvt_pk_bf16_f32 v123, v166, v167
	v_cvt_pk_bf16_f32 v124, v168, v169
	v_cvt_pk_bf16_f32 v125, v170, v171
	v_cvt_pk_bf16_f32 v126, v172, v173
	v_cvt_pk_bf16_f32 v127, v174, v175
	v_permlane32_swap_b32_e32 v112, v114
	v_permlane32_swap_b32_e32 v113, v115
	v_permlane32_swap_b32_e32 v116, v118
	v_permlane32_swap_b32_e32 v117, v119
	v_permlane32_swap_b32_e32 v120, v122
	v_permlane32_swap_b32_e32 v121, v123
	v_permlane32_swap_b32_e32 v124, v126
	v_permlane32_swap_b32_e32 v125, v127
	s_lshl_b32 s75, s75, 14
	v_add_u32_e32 v226, s75, v187
	ds_read_b64_tr_b16 v[160:161], v226 offset:0
	ds_read_b64_tr_b16 v[162:163], v226 offset:0x800
	ds_read_b64_tr_b16 v[164:165], v226 offset:0x1000
	ds_read_b64_tr_b16 v[166:167], v226 offset:0x1800
	ds_read_b64_tr_b16 v[168:169], v226 offset:0x2000
	ds_read_b64_tr_b16 v[170:171], v226 offset:0x2800
	ds_read_b64_tr_b16 v[172:173], v226 offset:0x3000
	ds_read_b64_tr_b16 v[174:175], v226 offset:0x3800
	s_setprio 1
	s_waitcnt lgkmcnt(6)
	v_mfma_f32_32x32x16_bf16 v[48:63], v[112:115], v[160:163], v[48:63]
	s_waitcnt lgkmcnt(4)
	v_mfma_f32_32x32x16_bf16 v[48:63], v[116:119], v[164:167], v[48:63]
	s_waitcnt lgkmcnt(2)
	v_mfma_f32_32x32x16_bf16 v[48:63], v[120:123], v[168:171], v[48:63]
	s_waitcnt lgkmcnt(0)
	v_mfma_f32_32x32x16_bf16 v[48:63], v[124:127], v[172:175], v[48:63]
	s_setprio 0
	v_max3_f32 v160, v80, v81, v82
	v_max3_f32 v161, v64, v65, v66
	v_max_f32_e32 v162, v79, v79
	v_max3_f32 v160, v160, v83, v84
	v_max3_f32 v161, v161, v67, v68
	v_max_f32_e32 v163, v95, v95
	v_max3_f32 v160, v160, v85, v86
	v_max3_f32 v161, v161, v69, v70
	v_max_f32_e32 v162, v163, v162
	v_max3_f32 v160, v160, v87, v88
	v_max3_f32 v161, v161, v71, v72
	s_nop 0
	v_max3_f32 v160, v160, v89, v90
	v_max3_f32 v161, v161, v73, v74
	s_nop 0
	v_max3_f32 v160, v160, v91, v92
	v_max3_f32 v161, v161, v75, v76
	s_nop 0
	v_max3_f32 v160, v160, v93, v94
	v_max3_f32 v161, v161, v77, v78
	s_nop 0
	v_max3_f32 v160, v160, v161, v162
	s_nop 0
	v_mov_b32_e32 v161, v160
	s_nop 1
	v_permlane32_swap_b32_e32 v160, v161
	v_max_f32_e32 v161, v161, v161
	v_max_f32_e32 v160, v160, v160
	v_max_f32_e32 v218, v160, v161
	ds_read_b64_tr_b16 v[160:161], v226 offset:0x200
	ds_read_b64_tr_b16 v[162:163], v226 offset:0xa00
	ds_read_b64_tr_b16 v[164:165], v226 offset:0x1200
	ds_read_b64_tr_b16 v[166:167], v226 offset:0x1a00
	ds_read_b64_tr_b16 v[168:169], v226 offset:0x2200
	ds_read_b64_tr_b16 v[170:171], v226 offset:0x2a00
	ds_read_b64_tr_b16 v[172:173], v226 offset:0x3200
	ds_read_b64_tr_b16 v[174:175], v226 offset:0x3a00
	s_setprio 1
	s_waitcnt lgkmcnt(6)
	v_mfma_f32_32x32x16_bf16 v[32:47], v[112:115], v[160:163], v[32:47]
	s_waitcnt lgkmcnt(4)
	v_mfma_f32_32x32x16_bf16 v[32:47], v[116:119], v[164:167], v[32:47]
	s_waitcnt lgkmcnt(2)
	v_mfma_f32_32x32x16_bf16 v[32:47], v[120:123], v[168:171], v[32:47]
	s_waitcnt lgkmcnt(0)
	v_mfma_f32_32x32x16_bf16 v[32:47], v[124:127], v[172:175], v[32:47]
	s_setprio 0
	v_sub_f32_e32 v160, v218, v222
	v_cmp_ge_f32_e32 vcc, s71, v160
	s_cmp_eq_u64 vcc, exec
	v_max_f32_e32 v160, v222, v222
	v_max_f32_e32 v225, v160, v218
	s_cselect_b64 s[0:1], -1, 0
	v_cndmask_b32_e64 v218, v225, v222, s[0:1]
	v_mul_f32_e32 v161, 0xbe38aa3b, v218
	v_fma_f32 v80, v80, v197, v161
	v_fma_f32 v81, v81, v197, v161
	v_fma_f32 v82, v82, v197, v161
	v_fma_f32 v83, v83, v197, v161
	v_fma_f32 v84, v84, v197, v161
	v_fma_f32 v85, v85, v197, v161
	v_fma_f32 v86, v86, v197, v161
	v_fma_f32 v87, v87, v197, v161
	v_fma_f32 v88, v88, v197, v161
	v_fma_f32 v89, v89, v197, v161
	v_fma_f32 v90, v90, v197, v161
	v_fma_f32 v91, v91, v197, v161
	v_fma_f32 v92, v92, v197, v161
	v_fma_f32 v93, v93, v197, v161
	v_fma_f32 v94, v94, v197, v161
	v_fma_f32 v95, v95, v197, v161
	v_fma_f32 v174, v64, v197, v161
	v_fma_f32 v175, v65, v197, v161
	v_fma_f32 v172, v66, v197, v161
	v_fma_f32 v173, v67, v197, v161
	v_fma_f32 v170, v68, v197, v161
	v_fma_f32 v171, v69, v197, v161
	v_fma_f32 v168, v70, v197, v161
	v_fma_f32 v169, v71, v197, v161
	v_fma_f32 v166, v72, v197, v161
	v_fma_f32 v167, v73, v197, v161
	v_fma_f32 v164, v74, v197, v161
	v_fma_f32 v165, v75, v197, v161
	v_fma_f32 v162, v76, v197, v161
	v_fma_f32 v163, v77, v197, v161
	v_fma_f32 v160, v78, v197, v161
	v_fma_f32 v161, v79, v197, v161
	ds_read_b64_tr_b16 v[64:65], v226 offset:0x400
	ds_read_b64_tr_b16 v[66:67], v226 offset:0xc00
	ds_read_b64_tr_b16 v[68:69], v226 offset:0x1400
	ds_read_b64_tr_b16 v[70:71], v226 offset:0x1c00
	ds_read_b64_tr_b16 v[72:73], v226 offset:0x2400
	ds_read_b64_tr_b16 v[74:75], v226 offset:0x2c00
	ds_read_b64_tr_b16 v[76:77], v226 offset:0x3400
	ds_read_b64_tr_b16 v[78:79], v226 offset:0x3c00
	s_setprio 1
	s_waitcnt lgkmcnt(6)
	v_mfma_f32_32x32x16_bf16 v[16:31], v[112:115], v[64:67], v[16:31]
	s_waitcnt lgkmcnt(4)
	v_mfma_f32_32x32x16_bf16 v[16:31], v[116:119], v[68:71], v[16:31]
	s_waitcnt lgkmcnt(2)
	v_mfma_f32_32x32x16_bf16 v[16:31], v[120:123], v[72:75], v[16:31]
	s_waitcnt lgkmcnt(0)
	v_mfma_f32_32x32x16_bf16 v[16:31], v[124:127], v[76:79], v[16:31]
	s_setprio 0
	ds_read_b64_tr_b16 v[64:65], v226 offset:0x600
	ds_read_b64_tr_b16 v[66:67], v226 offset:0xe00
	ds_read_b64_tr_b16 v[68:69], v226 offset:0x1600
	ds_read_b64_tr_b16 v[70:71], v226 offset:0x1e00
	ds_read_b64_tr_b16 v[72:73], v226 offset:0x2600
	ds_read_b64_tr_b16 v[74:75], v226 offset:0x2e00
	ds_read_b64_tr_b16 v[76:77], v226 offset:0x3600
	ds_read_b64_tr_b16 v[78:79], v226 offset:0x3e00
	s_setprio 1
	s_waitcnt lgkmcnt(6)
	v_mfma_f32_32x32x16_bf16 v[0:15], v[112:115], v[64:67], v[0:15]
	s_waitcnt lgkmcnt(4)
	v_mfma_f32_32x32x16_bf16 v[0:15], v[116:119], v[68:71], v[0:15]
	s_waitcnt lgkmcnt(2)
	v_mfma_f32_32x32x16_bf16 v[0:15], v[120:123], v[72:75], v[0:15]
	s_waitcnt lgkmcnt(0)
	v_mfma_f32_32x32x16_bf16 v[0:15], v[124:127], v[76:79], v[0:15]
	s_setprio 0
	v_sub_f32_e32 v112, v222, v225
	v_mul_f32_e32 v112, 0x3e38aa3b, v112
	v_exp_f32_e32 v112, v112
	s_nop 0
	v_cndmask_b32_e64 v112, v112, 1.0, s[0:1]
	s_waitcnt vmcnt(0)
	s_barrier
	s_cmp_gt_u32 s74, 28
	s_cselect_b64 s[48:49], -1, 0
	s_and_b64 vcc, exec, s[48:49]
	s_cbranch_vccnz .LBB0_1037
	s_add_i32 s77, s77, s33
	v_lshl_add_u64 v[64:65], v[176:177], 0, s[14:15]
	s_add_i32 m0, s77, 0xc000
	s_add_i32 s75, s51, s75
	global_load_lds_dwordx4 v[64:65], off
	v_lshl_add_u64 v[64:65], v[178:179], 0, s[34:35]
	s_mov_b32 m0, s75
	s_nop 0
	global_load_lds_dwordx4 v[64:65], off
	v_lshl_add_u64 v[64:65], v[180:181], 0, s[34:35]
	s_add_i32 m0, s75, 0x2000
	s_nop 0
	global_load_lds_dwordx4 v[64:65], off
.LBB0_1037:
	v_cmp_gt_f32_e32 vcc, 1.0, v112
	s_cbranch_vccz .LBB0_1041
	s_and_saveexec_b64 s[0:1], s[4:5]
	ds_write_b32 v215, v112 offset:128
	s_or_b64 exec, exec, s[0:1]
	s_waitcnt lgkmcnt(0)
	v_add_u32_e32 v76, s50, v188
	ds_read_b128 v[64:67], v76 offset:224
	ds_read_b128 v[68:71], v76 offset:192
	ds_read_b128 v[72:75], v76 offset:160
	ds_read_b128 v[76:79], v76 offset:128
	s_waitcnt lgkmcnt(0)
	v_pk_mul_f32 v[60:61], v[60:61], v[64:65]
	v_pk_mul_f32 v[56:57], v[56:57], v[68:69]
	v_pk_mul_f32 v[52:53], v[52:53], v[72:73]
	v_pk_mul_f32 v[62:63], v[62:63], v[66:67]
	v_pk_mul_f32 v[58:59], v[58:59], v[70:71]
	v_pk_mul_f32 v[54:55], v[54:55], v[74:75]
	v_pk_mul_f32 v[50:51], v[50:51], v[78:79]
	v_pk_mul_f32 v[48:49], v[48:49], v[76:77]
	v_pk_mul_f32 v[44:45], v[44:45], v[64:65]
	v_pk_mul_f32 v[40:41], v[40:41], v[68:69]
	v_pk_mul_f32 v[36:37], v[36:37], v[72:73]
	v_pk_mul_f32 v[46:47], v[46:47], v[66:67]
	v_pk_mul_f32 v[42:43], v[42:43], v[70:71]
	v_pk_mul_f32 v[38:39], v[38:39], v[74:75]
	v_pk_mul_f32 v[34:35], v[34:35], v[78:79]
	v_pk_mul_f32 v[32:33], v[32:33], v[76:77]
	v_pk_mul_f32 v[28:29], v[28:29], v[64:65]
	v_pk_mul_f32 v[24:25], v[24:25], v[68:69]
	v_pk_mul_f32 v[20:21], v[20:21], v[72:73]
	v_pk_mul_f32 v[30:31], v[30:31], v[66:67]
	v_pk_mul_f32 v[26:27], v[26:27], v[70:71]
	v_pk_mul_f32 v[22:23], v[22:23], v[74:75]
	v_pk_mul_f32 v[18:19], v[18:19], v[78:79]
	v_pk_mul_f32 v[16:17], v[16:17], v[76:77]
	v_pk_mul_f32 v[12:13], v[12:13], v[64:65]
	v_pk_mul_f32 v[8:9], v[8:9], v[68:69]
	v_pk_mul_f32 v[4:5], v[4:5], v[72:73]
	v_pk_mul_f32 v[14:15], v[14:15], v[66:67]
	v_pk_mul_f32 v[10:11], v[10:11], v[70:71]
	v_pk_mul_f32 v[6:7], v[6:7], v[74:75]
	v_pk_mul_f32 v[2:3], v[2:3], v[78:79]
	v_pk_mul_f32 v[0:1], v[0:1], v[76:77]

.LBB0_1054:
	v_exp_f32_e32 v227, v88
	v_exp_f32_e32 v232, v89
	s_add_i32 s0, s76, 1
	s_cmp_lg_u32 s76, 2
	s_cselect_b32 s36, s0, 0
	v_exp_f32_e32 v120, v80
	v_exp_f32_e32 v121, v81
	v_exp_f32_e32 v122, v82
	v_exp_f32_e32 v123, v83
	v_exp_f32_e32 v124, v84
	v_exp_f32_e32 v125, v85
	v_exp_f32_e32 v126, v86
	v_exp_f32_e32 v127, v87
	v_exp_f32_e32 v233, v90
	v_exp_f32_e32 v234, v91
	v_exp_f32_e32 v235, v92
	v_exp_f32_e32 v236, v93
	v_exp_f32_e32 v237, v94
	v_exp_f32_e32 v238, v95
	s_setprio 1
	v_lshl_add_u32 v230, s36, 13, v190
	v_add_u32_e32 v68, v230, v191
	ds_read_b128 v[64:67], v68 offset:49152
	ds_read_b128 v[68:71], v68 offset:53248
	v_add_u32_e32 v116, v230, v192
	ds_read_b128 v[112:115], v116 offset:49152
	ds_read_b128 v[116:119], v116 offset:53248
	s_waitcnt lgkmcnt(0)
	v_mfma_f32_32x32x16_bf16 v[80:95], v[64:67], v[108:111], 0
	v_mfma_f32_32x32x16_bf16 v[64:79], v[68:71], v[108:111], 0
	v_mfma_f32_32x32x16_bf16 v[80:95], v[112:115], v[104:107], v[80:95]
	v_mfma_f32_32x32x16_bf16 v[64:79], v[116:119], v[104:107], v[64:79]
	v_add_u32_e32 v116, v230, v193
	ds_read_b128 v[112:115], v116 offset:49152
	ds_read_b128 v[116:119], v116 offset:53248
	s_waitcnt lgkmcnt(0)
	v_mfma_f32_32x32x16_bf16 v[80:95], v[112:115], v[100:103], v[80:95]
	v_mfma_f32_32x32x16_bf16 v[64:79], v[116:119], v[100:103], v[64:79]
	v_add_u32_e32 v116, v230, v194
	ds_read_b128 v[112:115], v116 offset:49152
	ds_read_b128 v[116:119], v116 offset:53248
	s_waitcnt lgkmcnt(0)
	v_mfma_f32_32x32x16_bf16 v[80:95], v[112:115], v[96:99], v[80:95]
	v_mfma_f32_32x32x16_bf16 v[64:79], v[116:119], v[96:99], v[64:79]
	s_setprio 0
	v_exp_f32_e32 v166, v166
	v_exp_f32_e32 v167, v167
	v_add_f32_e32 v112, v120, v166
	v_add_f32_e32 v113, v121, v167
	v_exp_f32_e32 v168, v168
	v_add_f32_e32 v112, v112, v122
	v_add_f32_e32 v113, v113, v123
	v_exp_f32_e32 v169, v169
	v_add_f32_e32 v112, v112, v168
	v_add_f32_e32 v113, v113, v169
	v_exp_f32_e32 v170, v170
	v_add_f32_e32 v112, v112, v124
	v_add_f32_e32 v113, v113, v125
	v_exp_f32_e32 v171, v171
	v_add_f32_e32 v112, v112, v170
	v_add_f32_e32 v113, v113, v171
	v_exp_f32_e32 v172, v172
	v_add_f32_e32 v112, v112, v126
	v_add_f32_e32 v113, v113, v127
	v_exp_f32_e32 v173, v173
	v_add_f32_e32 v112, v112, v172
	v_add_f32_e32 v113, v113, v173
	v_exp_f32_e32 v174, v174
	v_add_f32_e32 v112, v112, v227
	v_add_f32_e32 v113, v113, v232
	v_exp_f32_e32 v175, v175
	v_add_f32_e32 v112, v112, v174
	v_add_f32_e32 v113, v113, v175
	v_exp_f32_e32 v176, v176
	v_add_f32_e32 v112, v112, v233
	v_add_f32_e32 v113, v113, v234
	v_exp_f32_e32 v177, v177
	v_add_f32_e32 v112, v112, v176
	v_add_f32_e32 v113, v113, v177
	v_exp_f32_e32 v178, v178
	v_add_f32_e32 v112, v112, v235
	v_add_f32_e32 v113, v113, v236
	v_exp_f32_e32 v179, v179
	v_exp_f32_e32 v180, v180
	v_exp_f32_e32 v181, v181
	v_add_f32_e32 v112, v112, v178
	v_add_f32_e32 v113, v113, v179
	s_nop 0
	v_add_f32_e32 v112, v112, v237
	v_add_f32_e32 v113, v113, v238
	s_nop 0
	v_add_f32_e32 v112, v112, v180
	v_add_f32_e32 v113, v113, v181
	s_nop 0
	v_add_f32_e32 v230, v112, v113
	v_cvt_pk_bf16_f32 v112, v120, v121
	v_cvt_pk_bf16_f32 v113, v122, v123
	v_cvt_pk_bf16_f32 v114, v124, v125
	v_cvt_pk_bf16_f32 v115, v126, v127
	v_cvt_pk_bf16_f32 v116, v227, v232
	s_nop 0
	v_mov_b32_e32 v231, v230
	s_nop 1
	v_permlane32_swap_b32_e32 v230, v231
	v_cvt_pk_bf16_f32 v117, v233, v234
	v_cvt_pk_bf16_f32 v118, v235, v236
	v_cvt_pk_bf16_f32 v119, v237, v238
	v_cvt_pk_bf16_f32 v120, v166, v167
	v_cvt_pk_bf16_f32 v121, v168, v169
	v_cvt_pk_bf16_f32 v122, v170, v171
	v_cvt_pk_bf16_f32 v123, v172, v173
	v_cvt_pk_bf16_f32 v124, v174, v175
	v_cvt_pk_bf16_f32 v125, v176, v177
	v_cvt_pk_bf16_f32 v126, v178, v179
	v_cvt_pk_bf16_f32 v127, v180, v181
	v_permlane32_swap_b32_e32 v112, v114
	v_permlane32_swap_b32_e32 v113, v115
	v_permlane32_swap_b32_e32 v116, v118
	v_permlane32_swap_b32_e32 v117, v119
	v_permlane32_swap_b32_e32 v120, v122
	v_permlane32_swap_b32_e32 v121, v123
	v_permlane32_swap_b32_e32 v124, v126
	v_permlane32_swap_b32_e32 v125, v127
	s_lshl_b32 s41, s76, 14
	v_add_u32_e32 v233, s41, v187
	ds_read_b64_tr_b16 v[166:167], v233 offset:0
	ds_read_b64_tr_b16 v[168:169], v233 offset:0x800
	ds_read_b64_tr_b16 v[170:171], v233 offset:0x1000
	ds_read_b64_tr_b16 v[172:173], v233 offset:0x1800
	ds_read_b64_tr_b16 v[174:175], v233 offset:0x2000
	ds_read_b64_tr_b16 v[176:177], v233 offset:0x2800
	ds_read_b64_tr_b16 v[178:179], v233 offset:0x3000
	ds_read_b64_tr_b16 v[180:181], v233 offset:0x3800
	s_setprio 1
	s_waitcnt lgkmcnt(6)
	v_mfma_f32_32x32x16_bf16 v[48:63], v[112:115], v[166:169], v[48:63]
	s_waitcnt lgkmcnt(4)
	v_mfma_f32_32x32x16_bf16 v[48:63], v[116:119], v[170:173], v[48:63]
	s_waitcnt lgkmcnt(2)
	v_mfma_f32_32x32x16_bf16 v[48:63], v[120:123], v[174:177], v[48:63]
	s_waitcnt lgkmcnt(0)
	v_mfma_f32_32x32x16_bf16 v[48:63], v[124:127], v[178:181], v[48:63]
	s_setprio 0
	v_max3_f32 v166, v80, v81, v82
	v_max3_f32 v167, v64, v65, v66
	v_max_f32_e32 v168, v79, v79
	v_max3_f32 v166, v166, v83, v84
	v_max3_f32 v167, v167, v67, v68
	v_max_f32_e32 v169, v95, v95
	v_max3_f32 v166, v166, v85, v86
	v_max3_f32 v167, v167, v69, v70
	v_max_f32_e32 v168, v169, v168
	v_max3_f32 v166, v166, v87, v88
	v_max3_f32 v167, v167, v71, v72
	s_nop 0
	v_max3_f32 v166, v166, v89, v90
	v_max3_f32 v167, v167, v73, v74
	s_nop 0
	v_max3_f32 v166, v166, v91, v92
	v_max3_f32 v167, v167, v75, v76
	s_nop 0
	v_max3_f32 v166, v166, v93, v94
	v_max3_f32 v167, v167, v77, v78
	s_nop 0
	v_max3_f32 v166, v166, v167, v168
	s_nop 0
	v_mov_b32_e32 v167, v166
	s_nop 1
	v_permlane32_swap_b32_e32 v166, v167
	v_max_f32_e32 v167, v167, v167
	v_max_f32_e32 v166, v166, v166
	v_max_f32_e32 v227, v166, v167
	ds_read_b64_tr_b16 v[166:167], v233 offset:0x200
	ds_read_b64_tr_b16 v[168:169], v233 offset:0xa00
	ds_read_b64_tr_b16 v[170:171], v233 offset:0x1200
	ds_read_b64_tr_b16 v[172:173], v233 offset:0x1a00
	ds_read_b64_tr_b16 v[174:175], v233 offset:0x2200
	ds_read_b64_tr_b16 v[176:177], v233 offset:0x2a00
	ds_read_b64_tr_b16 v[178:179], v233 offset:0x3200
	ds_read_b64_tr_b16 v[180:181], v233 offset:0x3a00
	s_setprio 1
	s_waitcnt lgkmcnt(6)
	v_mfma_f32_32x32x16_bf16 v[32:47], v[112:115], v[166:169], v[32:47]
	s_waitcnt lgkmcnt(4)
	v_mfma_f32_32x32x16_bf16 v[32:47], v[116:119], v[170:173], v[32:47]
	s_waitcnt lgkmcnt(2)
	v_mfma_f32_32x32x16_bf16 v[32:47], v[120:123], v[174:177], v[32:47]
	s_waitcnt lgkmcnt(0)
	v_mfma_f32_32x32x16_bf16 v[32:47], v[124:127], v[178:181], v[32:47]
	s_setprio 0
	v_sub_f32_e32 v166, v227, v229
	v_cmp_ge_f32_e32 vcc, s71, v166
	s_cmp_eq_u64 vcc, exec
	v_max_f32_e32 v166, v229, v229
	v_max_f32_e32 v232, v166, v227
	s_cselect_b64 s[0:1], -1, 0
	v_cndmask_b32_e64 v227, v232, v229, s[0:1]
	v_mul_f32_e32 v167, 0xbe38aa3b, v227
	v_fma_f32 v80, v80, v197, v167
	v_fma_f32 v81, v81, v197, v167
	v_fma_f32 v82, v82, v197, v167
	v_fma_f32 v83, v83, v197, v167
	v_fma_f32 v84, v84, v197, v167
	v_fma_f32 v85, v85, v197, v167
	v_fma_f32 v86, v86, v197, v167
	v_fma_f32 v87, v87, v197, v167
	v_fma_f32 v88, v88, v197, v167
	v_fma_f32 v89, v89, v197, v167
	v_fma_f32 v90, v90, v197, v167
	v_fma_f32 v91, v91, v197, v167
	v_fma_f32 v92, v92, v197, v167
	v_fma_f32 v93, v93, v197, v167
	v_fma_f32 v94, v94, v197, v167
	v_fma_f32 v95, v95, v197, v167
	v_fma_f32 v180, v64, v197, v167
	v_fma_f32 v181, v65, v197, v167
	v_fma_f32 v178, v66, v197, v167
	v_fma_f32 v179, v67, v197, v167
	v_fma_f32 v176, v68, v197, v167
	v_fma_f32 v177, v69, v197, v167
	v_fma_f32 v174, v70, v197, v167
	v_fma_f32 v175, v71, v197, v167
	v_fma_f32 v172, v72, v197, v167
	v_fma_f32 v173, v73, v197, v167
	v_fma_f32 v170, v74, v197, v167
	v_fma_f32 v171, v75, v197, v167
	v_fma_f32 v168, v76, v197, v167
	v_fma_f32 v169, v77, v197, v167
	v_fma_f32 v166, v78, v197, v167
	v_fma_f32 v167, v79, v197, v167
	ds_read_b64_tr_b16 v[64:65], v233 offset:0x400
	ds_read_b64_tr_b16 v[66:67], v233 offset:0xc00
	ds_read_b64_tr_b16 v[68:69], v233 offset:0x1400
	ds_read_b64_tr_b16 v[70:71], v233 offset:0x1c00
	ds_read_b64_tr_b16 v[72:73], v233 offset:0x2400
	ds_read_b64_tr_b16 v[74:75], v233 offset:0x2c00
	ds_read_b64_tr_b16 v[76:77], v233 offset:0x3400
	ds_read_b64_tr_b16 v[78:79], v233 offset:0x3c00
	s_setprio 1
	s_waitcnt lgkmcnt(6)
	v_mfma_f32_32x32x16_bf16 v[16:31], v[112:115], v[64:67], v[16:31]
	s_waitcnt lgkmcnt(4)
	v_mfma_f32_32x32x16_bf16 v[16:31], v[116:119], v[68:71], v[16:31]
	s_waitcnt lgkmcnt(2)
	v_mfma_f32_32x32x16_bf16 v[16:31], v[120:123], v[72:75], v[16:31]
	s_waitcnt lgkmcnt(0)
	v_mfma_f32_32x32x16_bf16 v[16:31], v[124:127], v[76:79], v[16:31]
	s_setprio 0
	ds_read_b64_tr_b16 v[64:65], v233 offset:0x600
	ds_read_b64_tr_b16 v[66:67], v233 offset:0xe00
	ds_read_b64_tr_b16 v[68:69], v233 offset:0x1600
	ds_read_b64_tr_b16 v[70:71], v233 offset:0x1e00
	ds_read_b64_tr_b16 v[72:73], v233 offset:0x2600
	ds_read_b64_tr_b16 v[74:75], v233 offset:0x2e00
	ds_read_b64_tr_b16 v[76:77], v233 offset:0x3600
	ds_read_b64_tr_b16 v[78:79], v233 offset:0x3e00
	s_setprio 1
	s_waitcnt lgkmcnt(6)
	v_mfma_f32_32x32x16_bf16 v[0:15], v[112:115], v[64:67], v[0:15]
	s_waitcnt lgkmcnt(4)
	v_mfma_f32_32x32x16_bf16 v[0:15], v[116:119], v[68:71], v[0:15]
	s_waitcnt lgkmcnt(2)
	v_mfma_f32_32x32x16_bf16 v[0:15], v[120:123], v[72:75], v[0:15]
	s_waitcnt lgkmcnt(0)
	v_mfma_f32_32x32x16_bf16 v[0:15], v[124:127], v[76:79], v[0:15]
	s_setprio 0
	v_sub_f32_e32 v112, v229, v232
	v_mul_f32_e32 v112, 0x3e38aa3b, v112
	v_exp_f32_e32 v112, v112
	s_nop 0
	v_cndmask_b32_e64 v112, v112, 1.0, s[0:1]
	s_waitcnt vmcnt(0)
	s_barrier
	s_cmp_gt_u32 s37, 28
	s_cselect_b64 s[38:39], -1, 0
	s_and_b64 vcc, exec, s[38:39]
	s_cbranch_vccnz .LBB0_1056
	s_add_i32 s40, s40, s74
	v_lshl_add_u64 v[64:65], v[160:161], 0, s[60:61]
	s_add_i32 m0, s40, 0xc000
	s_add_i32 s40, s75, s41
	global_load_lds_dwordx4 v[64:65], off
	v_lshl_add_u64 v[64:65], v[162:163], 0, s[34:35]
	s_mov_b32 m0, s40
	s_nop 0
	global_load_lds_dwordx4 v[64:65], off
	v_lshl_add_u64 v[64:65], v[164:165], 0, s[34:35]
	s_add_i32 m0, s40, 0x2000
	s_nop 0
	global_load_lds_dwordx4 v[64:65], off
.LBB0_1056:
	v_cmp_gt_f32_e32 vcc, 1.0, v112
	s_cbranch_vccz .LBB0_1060
	s_and_saveexec_b64 s[0:1], s[4:5]
	ds_write_b32 v223, v112 offset:128
	s_or_b64 exec, exec, s[0:1]
	s_waitcnt lgkmcnt(0)
	v_add_u32_e32 v76, s33, v188
	ds_read_b128 v[64:67], v76 offset:224
	ds_read_b128 v[68:71], v76 offset:192
	ds_read_b128 v[72:75], v76 offset:160
	ds_read_b128 v[76:79], v76 offset:128
	s_waitcnt lgkmcnt(0)
	v_pk_mul_f32 v[60:61], v[60:61], v[64:65]
	v_pk_mul_f32 v[56:57], v[56:57], v[68:69]
	v_pk_mul_f32 v[52:53], v[52:53], v[72:73]
	v_pk_mul_f32 v[62:63], v[62:63], v[66:67]
	v_pk_mul_f32 v[58:59], v[58:59], v[70:71]
	v_pk_mul_f32 v[54:55], v[54:55], v[74:75]
	v_pk_mul_f32 v[50:51], v[50:51], v[78:79]
	v_pk_mul_f32 v[48:49], v[48:49], v[76:77]
	v_pk_mul_f32 v[44:45], v[44:45], v[64:65]
	v_pk_mul_f32 v[40:41], v[40:41], v[68:69]
	v_pk_mul_f32 v[36:37], v[36:37], v[72:73]
	v_pk_mul_f32 v[46:47], v[46:47], v[66:67]
	v_pk_mul_f32 v[42:43], v[42:43], v[70:71]
	v_pk_mul_f32 v[38:39], v[38:39], v[74:75]
	v_pk_mul_f32 v[34:35], v[34:35], v[78:79]
	v_pk_mul_f32 v[32:33], v[32:33], v[76:77]
	v_pk_mul_f32 v[28:29], v[28:29], v[64:65]
	v_pk_mul_f32 v[24:25], v[24:25], v[68:69]
	v_pk_mul_f32 v[20:21], v[20:21], v[72:73]
	v_pk_mul_f32 v[30:31], v[30:31], v[66:67]
	v_pk_mul_f32 v[26:27], v[26:27], v[70:71]
	v_pk_mul_f32 v[22:23], v[22:23], v[74:75]
	v_pk_mul_f32 v[18:19], v[18:19], v[78:79]
	v_pk_mul_f32 v[16:17], v[16:17], v[76:77]
	v_pk_mul_f32 v[12:13], v[12:13], v[64:65]
	v_pk_mul_f32 v[8:9], v[8:9], v[68:69]
	v_pk_mul_f32 v[4:5], v[4:5], v[72:73]
	v_pk_mul_f32 v[14:15], v[14:15], v[66:67]
	v_pk_mul_f32 v[10:11], v[10:11], v[70:71]
	v_pk_mul_f32 v[6:7], v[6:7], v[74:75]
	v_pk_mul_f32 v[2:3], v[2:3], v[78:79]
	v_pk_mul_f32 v[0:1], v[0:1], v[76:77]
